# v75: v68 + one static priority raise through G1/mixers/G2/LN1/G3 for the workgroup that is second on its CU (CU census), reset before PEER
# baseline (speedup 1.0000x reference)
.LBB0_295:
	v_readlane_b32 s98, v255, 62
	s_nop 0
	s_cmp_lg_u32 s98, 0x7fff
	s_cbranch_scc1 .Lgp_skip
	s_setprio 1

.LBB0_832:
	s_or_b64 exec, exec, s[0:1]
	s_setprio 0
	s_waitcnt lgkmcnt(0)
	v_mov_b32_e32 v2, v160
	s_barrier
	v_mov_b32_e32 v4, 0
	v_and_b32_e32 v3, 63, v2
	v_cmp_gt_u32_e64 s[2:3], 16, v3
	v_cmp_lt_u32_e32 vcc, 15, v3
	v_mov_b32_e32 v0, v3
	s_barrier
	s_and_saveexec_b64 s[0:1], vcc
	s_cbranch_execz .LBB0_852
	v_add_u32_e32 v0, -16, v3
	v_cmp_lt_u32_e32 vcc, 7, v0
	v_mov_b32_e32 v4, 1
	s_and_saveexec_b64 s[4:5], vcc
	s_cbranch_execz .LBB0_851
	v_subrev_u32_e32 v0, 24, v3
	v_cmp_lt_u32_e32 vcc, 4, v0
	v_mov_b32_e32 v4, 2
	s_and_saveexec_b64 s[6:7], vcc
	s_cbranch_execz .LBB0_850
	v_subrev_u32_e32 v0, 29, v3
	v_mov_b32_e32 v4, 3
	v_cmp_lt_u32_e32 vcc, 3, v0
	s_and_saveexec_b64 s[8:9], vcc
	s_cbranch_execz .LBB0_849
	v_subrev_u32_e32 v0, 33, v3
	v_cmp_lt_u32_e32 vcc, 2, v0
	v_mov_b32_e32 v4, 4
	s_and_saveexec_b64 s[10:11], vcc
	s_cbranch_execz .LBB0_848
	v_subrev_u32_e32 v0, 36, v3
	v_cmp_lt_u32_e32 vcc, 1, v0
	v_mov_b32_e32 v4, 5
	s_and_saveexec_b64 s[12:13], vcc
	s_cbranch_execz .LBB0_847
	v_subrev_u32_e32 v0, 38, v3
	v_cmp_lt_u32_e32 vcc, 1, v0
	v_mov_b32_e32 v4, 6
	s_and_saveexec_b64 s[24:25], vcc
	s_cbranch_execz .LBB0_846
	v_subrev_u32_e32 v0, 40, v3
	v_cmp_lt_u32_e32 vcc, 1, v0
	v_mov_b32_e32 v4, 7
	s_and_saveexec_b64 s[26:27], vcc
	s_cbranch_execz .LBB0_845
	v_subrev_u32_e32 v0, 42, v3
	v_cmp_lt_u32_e32 vcc, 7, v0
	s_and_saveexec_b64 s[28:29], vcc
	s_xor_b64 s[28:29], exec, s[28:29]
	v_subrev_u32_e32 v0, 50, v3
	s_or_saveexec_b64 s[28:29], s[28:29]
	v_mov_b32_e32 v4, 16
	s_xor_b64 exec, exec, s[28:29]
	v_subrev_u32_e32 v4, 34, v3
	v_mov_b32_e32 v0, 0
	s_or_b64 exec, exec, s[28:29]
